# v28 plus MLA softmax: loop-invariant cross-half lane address for the row-max exchange computed once in the MFMA wait slot instead of seven dependent VALU ops before ds_bpermute
# baseline (speedup 1.0000x reference)
; __device__ __forceinline__ float ex2(float x) { return __builtin_amdgcn_exp2f(x); }
; template <int DQK, int DV, int MODE, int VR> ...
;     ...
;                 float mx = fmaxf(p[0][0], p[1][0]);
; #pragma unroll
;                 for (int r = 1; r < 16; ++r) mx = fmaxf(mx, fmaxf(p[0][r], p[1][r]));
;                 mx = fmaxf(mx, __shfl_xor(mx, 32));
;                 const float mnew = fmaxf(mrun, mx * cscale), alpha = ex2(mrun - mnew); float ls = 0.f;
; #pragma unroll
;                 for (int kb = 0; kb < 2; ++kb)
; #pragma unroll
;                     for (int r = 0; r < 16; ++r) { const float e = ex2(p[kb][r] * cscale - mnew); p[kb][r] = e; ls += e; }
;                 lrun = lrun * alpha + ls;
;                 if (__any(mnew > mrun)) {
; #pragma unroll
;                     for (int b = 0; b < NBLK; ++b)
; #pragma unroll
;                         for (int r = 0; r < 16; ++r) o[b][r] *= alpha;
;                 }
.LBB0_740:
	v_xor_b32_e32 v183, 32, v195
	v_lshlrev_b32_e32 v183, 2, v183
	s_nop 8
	v_max3_f32 v0, v66, v67, v68
	v_max3_f32 v177, v82, v83, v84
	v_max3_f32 v0, v0, v69, v70
	v_max3_f32 v177, v177, v85, v86
	v_max3_f32 v0, v0, v71, v72
	v_max3_f32 v177, v177, v87, v88
	v_max3_f32 v0, v0, v73, v74
	v_max3_f32 v177, v177, v89, v90
	v_max3_f32 v0, v0, v75, v76
	v_max3_f32 v177, v177, v91, v92
	v_max3_f32 v0, v0, v77, v78
	v_max3_f32 v177, v177, v93, v94
	v_max3_f32 v0, v0, v79, v80
	v_max3_f32 v177, v177, v95, v96
	v_max_f32_e32 v0, v0, v81
	v_max_f32_e32 v177, v177, v97
	v_max_f32_e32 v0, v0, v177
	ds_bpermute_b32 v177, v183, v0
	s_waitcnt lgkmcnt(0)
	v_max_f32_e32 v177, v177, v177
	v_max_f32_e32 v0, v0, v177
	v_mul_f32_e32 v0, 0x3dd53b94, v0
	v_max_f32_e32 v177, v182, v182
	v_max_f32_e32 v177, v177, v0
	v_sub_f32_e32 v0, v182, v177
	v_exp_f32_e32 v0, v0
	v_cmp_gt_f32_e32 vcc, v177, v182
	s_cbranch_vccz .LBB0_742
	v_pk_mul_f32 v[64:65], v[64:65], v[0:1] op_sel_hi:[1,0]
	v_pk_mul_f32 v[62:63], v[62:63], v[0:1] op_sel_hi:[1,0]
	v_pk_mul_f32 v[60:61], v[60:61], v[0:1] op_sel_hi:[1,0]
	v_pk_mul_f32 v[58:59], v[58:59], v[0:1] op_sel_hi:[1,0]
	v_pk_mul_f32 v[56:57], v[56:57], v[0:1] op_sel_hi:[1,0]
	v_pk_mul_f32 v[54:55], v[54:55], v[0:1] op_sel_hi:[1,0]
	v_pk_mul_f32 v[52:53], v[52:53], v[0:1] op_sel_hi:[1,0]
	v_pk_mul_f32 v[50:51], v[50:51], v[0:1] op_sel_hi:[1,0]
	v_pk_mul_f32 v[48:49], v[48:49], v[0:1] op_sel_hi:[1,0]
	v_pk_mul_f32 v[46:47], v[46:47], v[0:1] op_sel_hi:[1,0]
	v_pk_mul_f32 v[44:45], v[44:45], v[0:1] op_sel_hi:[1,0]
	v_pk_mul_f32 v[42:43], v[42:43], v[0:1] op_sel_hi:[1,0]
	v_pk_mul_f32 v[40:41], v[40:41], v[0:1] op_sel_hi:[1,0]
	v_pk_mul_f32 v[38:39], v[38:39], v[0:1] op_sel_hi:[1,0]
	v_pk_mul_f32 v[36:37], v[36:37], v[0:1] op_sel_hi:[1,0]
	v_pk_mul_f32 v[34:35], v[34:35], v[0:1] op_sel_hi:[1,0]
	v_pk_mul_f32 v[32:33], v[32:33], v[0:1] op_sel_hi:[1,0]
	v_pk_mul_f32 v[30:31], v[30:31], v[0:1] op_sel_hi:[1,0]
	v_pk_mul_f32 v[28:29], v[28:29], v[0:1] op_sel_hi:[1,0]
	v_pk_mul_f32 v[26:27], v[26:27], v[0:1] op_sel_hi:[1,0]
	v_pk_mul_f32 v[24:25], v[24:25], v[0:1] op_sel_hi:[1,0]
	v_pk_mul_f32 v[22:23], v[22:23], v[0:1] op_sel_hi:[1,0]
	v_pk_mul_f32 v[20:21], v[20:21], v[0:1] op_sel_hi:[1,0]
	v_pk_mul_f32 v[18:19], v[18:19], v[0:1] op_sel_hi:[1,0]
	v_pk_mul_f32 v[16:17], v[16:17], v[0:1] op_sel_hi:[1,0]
	v_pk_mul_f32 v[14:15], v[14:15], v[0:1] op_sel_hi:[1,0]
	v_pk_mul_f32 v[12:13], v[12:13], v[0:1] op_sel_hi:[1,0]
	v_pk_mul_f32 v[10:11], v[10:11], v[0:1] op_sel_hi:[1,0]
	v_pk_mul_f32 v[8:9], v[8:9], v[0:1] op_sel_hi:[1,0]
	v_pk_mul_f32 v[6:7], v[6:7], v[0:1] op_sel_hi:[1,0]
	v_pk_mul_f32 v[4:5], v[4:5], v[0:1] op_sel_hi:[1,0]
	v_pk_mul_f32 v[2:3], v[2:3], v[0:1] op_sel_hi:[1,0]
